# hyena: filter spectra are stored plain and re-read with L1-bypassing loads by the same workgroup, so the all-thread L2 writeback+invalidate fence is replaced by a store drain before the barrier
# speedup vs baseline: 1.0161x; 1.0161x over previous
; __device__ __forceinline__ void fft_last_fwd(LAS cf* X, int tid, cf* KFW, float bias, float scale) {
;     ...
;     for (int i = 0; i < 8; ++i) { const int it = tid + 512 * i, g = it & 255, k = it >> 8, base = g * 64 + 4 * k;
;         cf e0 = X[PX(base)], e1 = X[PX(base + 1)], e2 = X[PX(base + 2)], e3 = X[PX(base + 3)];
;         bfly4_fwd(e0, e1, e2, e3);
;         if (KFW) { cf* o = KFW + (4 * k) * 256 + g; o[0] = mk2((e0.x + bias) * scale, e0.y * scale); o[256] = mk2((e1.x + bias) * scale, e1.y * scale); o[512] = mk2((e2.x + bias) * scale, e2.y * scale); o[768] = mk2((e3.x + bias) * scale, e3.y * scale); }
;         else { X[PX(base)] = e0; X[PX(base + 1)] = e1; X[PX(base + 2)] = e2; X[PX(base + 3)] = e3; } }
;     __syncthreads();
; __global__ void __launch_bounds__(NTHR, 2) fwd_mega(Args a) {
;     ...
;                 __threadfence(); __syncthreads();
.LBB0_527:
	v_add_u32_e32 v1, s4, v16
	v_ashrrev_i32_e32 v3, 6, v1
	v_and_b32_e32 v3, -4, v3
	v_add_u32_e32 v6, v3, v157
	v_ashrrev_i32_e32 v7, 6, v6
	v_lshlrev_b32_e32 v7, 3, v7
	v_lshlrev_b32_e32 v6, 3, v6
	v_add3_u32 v10, 0, v7, v6
	ds_read2_b64 v[6:9], v10 offset1:1
	ds_read2_b64 v[10:13], v10 offset0:2 offset1:3
	v_lshlrev_b32_e32 v140, 8, v3
	v_ashrrev_i32_e32 v141, 31, v140
	v_lshl_add_u64 v[140:141], v[140:141], 3, v[4:5]
	v_add_u32_e32 v1, 0x200, v1
	s_waitcnt lgkmcnt(0)
	v_pk_add_f32 v[14:15], v[6:7], v[10:11]
	v_pk_add_f32 v[6:7], v[6:7], v[10:11] neg_lo:[0,1] neg_hi:[0,1]
	v_pk_add_f32 v[10:11], v[8:9], v[12:13]
	v_pk_add_f32 v[8:9], v[8:9], v[12:13] neg_lo:[0,1] neg_hi:[0,1]
	v_pk_add_f32 v[12:13], v[14:15], v[10:11]
	v_pk_add_f32 v[10:11], v[14:15], v[10:11] neg_lo:[0,1] neg_hi:[0,1]
	v_add_f32_e32 v12, v2, v12
	v_pk_add_f32 v[14:15], v[6:7], v[8:9] op_sel:[0,1] op_sel_hi:[1,0]
	v_pk_mul_f32 v[12:13], v[12:13], s[22:23] op_sel_hi:[1,0]
	v_mov_b32_e32 v3, v7
	v_pk_add_f32 v[138:139], v[6:7], v[8:9] op_sel:[0,1] op_sel_hi:[1,0] neg_lo:[0,1] neg_hi:[0,1]
	global_store_dwordx2 v[140:141], v[12:13], off
	v_pk_add_f32 v[12:13], v[2:3], v[14:15]
	v_pk_add_f32 v[6:7], v[6:7], v[8:9] op_sel_hi:[1,0] neg_lo:[0,1] neg_hi:[0,1]
	v_add_f32_e32 v10, v2, v10
	v_mov_b32_e32 v13, v7
	v_pk_mul_f32 v[6:7], v[12:13], s[22:23] op_sel_hi:[1,0]
	global_store_dwordx2 v[140:141], v[6:7], off offset:2048
	v_pk_mul_f32 v[6:7], v[10:11], s[22:23] op_sel_hi:[1,0]
	v_add_co_u32_e32 v10, vcc, s96, v140
	v_mov_b32_e32 v139, v8
	s_nop 0
	v_addc_co_u32_e32 v11, vcc, 0, v141, vcc
	v_ashrrev_i32_e32 v1, 6, v1
	global_store_dwordx2 v[10:11], v[6:7], off
	v_pk_add_f32 v[6:7], v[2:3], v[138:139]
	v_and_b32_e32 v1, -4, v1
	v_pk_mul_f32 v[6:7], v[6:7], s[22:23] op_sel_hi:[1,0]
	v_add_u32_e32 v3, v1, v157
	global_store_dwordx2 v[10:11], v[6:7], off offset:2048
	v_ashrrev_i32_e32 v6, 6, v3
	v_lshlrev_b32_e32 v6, 3, v6
	v_lshlrev_b32_e32 v3, 3, v3
	v_add3_u32 v3, 0, v6, v3
	ds_read2_b64 v[6:9], v3 offset1:1
	ds_read2_b64 v[10:13], v3 offset0:2 offset1:3
	v_lshlrev_b32_e32 v140, 8, v1
	v_ashrrev_i32_e32 v141, 31, v140
	v_lshl_add_u64 v[140:141], v[140:141], 3, v[4:5]
	s_addk_i32 s4, 0x400
	s_waitcnt lgkmcnt(0)
	v_pk_add_f32 v[14:15], v[6:7], v[10:11]
	v_pk_add_f32 v[6:7], v[6:7], v[10:11] neg_lo:[0,1] neg_hi:[0,1]
	v_pk_add_f32 v[10:11], v[8:9], v[12:13]
	v_pk_add_f32 v[8:9], v[8:9], v[12:13] neg_lo:[0,1] neg_hi:[0,1]
	v_pk_add_f32 v[12:13], v[14:15], v[10:11]
	v_pk_add_f32 v[10:11], v[14:15], v[10:11] neg_lo:[0,1] neg_hi:[0,1]
	v_add_f32_e32 v12, v2, v12
	v_pk_add_f32 v[14:15], v[6:7], v[8:9] op_sel:[0,1] op_sel_hi:[1,0]
	v_pk_mul_f32 v[12:13], v[12:13], s[22:23] op_sel_hi:[1,0]
	v_mov_b32_e32 v3, v7
	v_pk_add_f32 v[138:139], v[6:7], v[8:9] op_sel:[0,1] op_sel_hi:[1,0] neg_lo:[0,1] neg_hi:[0,1]
	global_store_dwordx2 v[140:141], v[12:13], off
	v_pk_add_f32 v[12:13], v[2:3], v[14:15]
	v_pk_add_f32 v[6:7], v[6:7], v[8:9] op_sel_hi:[1,0] neg_lo:[0,1] neg_hi:[0,1]
	v_add_f32_e32 v10, v2, v10
	v_mov_b32_e32 v13, v7
	v_pk_mul_f32 v[6:7], v[12:13], s[22:23] op_sel_hi:[1,0]
	global_store_dwordx2 v[140:141], v[6:7], off offset:2048
	v_pk_mul_f32 v[6:7], v[10:11], s[22:23] op_sel_hi:[1,0]
	v_add_co_u32_e32 v10, vcc, 0x1000, v140
	v_mov_b32_e32 v139, v8
	s_nop 0
	v_addc_co_u32_e32 v11, vcc, 0, v141, vcc
	global_store_dwordx2 v[10:11], v[6:7], off
	v_pk_add_f32 v[6:7], v[2:3], v[138:139]
	s_cmpk_lg_i32 s4, 0x1000
	v_pk_mul_f32 v[6:7], v[6:7], s[22:23] op_sel_hi:[1,0]
	global_store_dwordx2 v[10:11], v[6:7], off offset:2048
	s_cbranch_scc1 .LBB0_527
	s_mov_b32 s48, 1
	s_mov_b64 s[46:47], 0
	s_and_b64 vcc, exec, s[36:37]
	s_waitcnt lgkmcnt(0)
	s_barrier
	s_cbranch_vccz .LBB0_509
	v_mov_b32_e32 v1, v209
	v_lshl_add_u64 v[0:1], s[12:13], 0, v[0:1]
	s_mov_b32 s78, s81
	v_lshl_add_u64 v[142:143], v[0:1], 0, s[66:67]
	s_lshl_b64 s[48:49], s[14:15], 15
	v_mov_b32_e32 v132, v124
	v_mov_b32_e32 v138, v133
	v_mov_b32_e32 v139, v124
	v_mov_b32_e32 v140, v135
	v_mov_b32_e32 v141, v134
	v_mov_b32_e32 v131, v130
	v_mov_b32_e32 v144, v129
	v_mov_b32_e32 v145, v129
	v_mov_b32_e32 v127, v126
	v_mov_b32_e32 v146, v128
	v_mov_b32_e32 v147, v128
	v_mov_b32_e32 v148, v128
	v_mov_b32_e32 v149, v126
	s_mov_b32 s12, 0
	s_mov_b64 s[4:5], -1
	s_waitcnt vmcnt(0)
	s_barrier
	s_branch .LBB0_531
